# chunk_prep forward substitution on the f32 matrix cores (v_mfma_f32_16x16x4_f32, 16x16 blocks; diagonal-block inverses by wave 0)
# speedup vs baseline: 1.0072x; 1.0072x over previous
; #define LAS __attribute__((address_space(3)))
; __device__ __forceinline__ void phase_chunk_prep(const Params& p, LAS unsigned char* lds, int wave_s) {
;     ...
;         if (tid < 256) {
;             const int col = tid; float sol[64];
; #pragma unroll
;             for (int i = 0; i < 64; ++i) sol[i] = 0.f;
; #pragma unroll
;             for (int i = 0; i < 64; ++i) {
;                 float s0 = RHS[i * 256 + col], s1 = 0.f, s2 = 0.f, s3 = 0.f;
; #pragma unroll
;                 for (int j4 = 0; j4 < (i + 3) / 4; ++j4) { const f32x4 a = *(const LAS f32x4*)(AM + i * 64 + 4 * j4);
;                     s0 -= a.x * sol[4 * j4]; s1 -= a.y * sol[4 * j4 + 1]; s2 -= a.z * sol[4 * j4 + 2]; s3 -= a.w * sol[4 * j4 + 3]; }
;                 sol[i] = (s0 + s1) + (s2 + s3);
;             }
.Lcpstage_n_end:
	s_lshr_b32 s84, s24, 6
	v_mbcnt_lo_u32_b32 v32, -1, 0
	v_mbcnt_hi_u32_b32 v32, -1, v32
	v_and_b32_e32 v33, 15, v32
	v_lshrrev_b32_e32 v34, 4, v32
	s_lshl_b32 s85, s84, 7
	v_lshl_add_u32 v84, v33, 2, s85
	v_lshl_add_u32 v84, v34, 12, v84
	v_add_u32_e32 v84, 0xc800, v84
	v_lshlrev_b32_e32 v85, 8, v33
	v_lshl_add_u32 v85, v34, 4, v85
	v_add_u32_e32 v85, 0x8800, v85
	v_mul_u32_u24_e32 v86, 80, v33
	v_lshl_add_u32 v86, v34, 4, v86
	v_add_u32_e32 v86, 0x22600, v86
	ds_read_b32 v0, v84
	ds_read_b32 v1, v84 offset:1024
	ds_read_b32 v2, v84 offset:2048
	ds_read_b32 v3, v84 offset:3072
	ds_read_b32 v4, v84 offset:16384
	ds_read_b32 v5, v84 offset:17408
	ds_read_b32 v6, v84 offset:18432
	ds_read_b32 v7, v84 offset:19456
	ds_read_b32 v8, v84 offset:32768
	ds_read_b32 v9, v84 offset:33792
	ds_read_b32 v10, v84 offset:34816
	ds_read_b32 v11, v84 offset:35840
	ds_read_b32 v12, v84 offset:49152
	ds_read_b32 v13, v84 offset:50176
	ds_read_b32 v14, v84 offset:51200
	ds_read_b32 v15, v84 offset:52224
	ds_read_b32 v16, v84 offset:64
	ds_read_b32 v17, v84 offset:1088
	ds_read_b32 v18, v84 offset:2112
	ds_read_b32 v19, v84 offset:3136
	ds_read_b32 v20, v84 offset:16448
	ds_read_b32 v21, v84 offset:17472
	ds_read_b32 v22, v84 offset:18496
	ds_read_b32 v23, v84 offset:19520
	ds_read_b32 v24, v84 offset:32832
	ds_read_b32 v25, v84 offset:33856
	ds_read_b32 v26, v84 offset:34880
	ds_read_b32 v27, v84 offset:35904
	ds_read_b32 v28, v84 offset:49216
	ds_read_b32 v29, v84 offset:50240
	ds_read_b32 v30, v84 offset:51264
	ds_read_b32 v31, v84 offset:52288
	ds_read_b128 v[148:151], v85 offset:4096
	ds_read_b128 v[152:155], v85 offset:8192
	ds_read_b128 v[156:159], v85 offset:8256
	ds_read_b128 v[160:163], v85 offset:12288
	ds_read_b128 v[164:167], v85 offset:12352
	ds_read_b128 v[168:171], v85 offset:12416
	s_cmp_lg_u32 s84, 0
	s_cbranch_scc1 .Lfm_not0
	v_mul_u32_u24_e32 v88, 0x1040, v34
	v_lshl_add_u32 v88, v33, 2, v88
	v_add_u32_e32 v88, 0x8800, v88
	ds_read_b32 v101, v88 offset:256
	ds_read_b32 v102, v88 offset:512
	ds_read_b32 v103, v88 offset:768
	ds_read_b32 v104, v88 offset:1024
	ds_read_b32 v105, v88 offset:1280
	ds_read_b32 v106, v88 offset:1536
	ds_read_b32 v107, v88 offset:1792
	ds_read_b32 v108, v88 offset:2048
	ds_read_b32 v109, v88 offset:2304
	ds_read_b32 v110, v88 offset:2560
	ds_read_b32 v111, v88 offset:2816
	ds_read_b32 v112, v88 offset:3072
	ds_read_b32 v113, v88 offset:3328
	ds_read_b32 v114, v88 offset:3584
	ds_read_b32 v115, v88 offset:3840
	v_mul_u32_u24_e32 v87, 0x500, v34
	v_lshl_add_u32 v87, v33, 2, v87
	v_add_u32_e32 v87, 0x22600, v87
	v_cmp_eq_u32_e32 vcc, 0, v33
	v_cmp_eq_u32_e64 s[86:87], 1, v33
	s_nop 0
	v_cndmask_b32_e64 v116, 0, 1.0, vcc
	v_cndmask_b32_e64 v117, 0, 1.0, s[86:87]
	v_cmp_eq_u32_e32 vcc, 2, v33
	v_cmp_eq_u32_e64 s[86:87], 3, v33
	s_nop 0
	v_cndmask_b32_e64 v118, 0, 1.0, vcc
	v_cndmask_b32_e64 v119, 0, 1.0, s[86:87]
	v_cmp_eq_u32_e32 vcc, 4, v33
	v_cmp_eq_u32_e64 s[86:87], 5, v33
	s_nop 0
	v_cndmask_b32_e64 v120, 0, 1.0, vcc
	v_cndmask_b32_e64 v121, 0, 1.0, s[86:87]
	v_cmp_eq_u32_e32 vcc, 6, v33
	v_cmp_eq_u32_e64 s[86:87], 7, v33
	s_nop 0
	v_cndmask_b32_e64 v122, 0, 1.0, vcc
	v_cndmask_b32_e64 v123, 0, 1.0, s[86:87]
	v_cmp_eq_u32_e32 vcc, 8, v33
	v_cmp_eq_u32_e64 s[86:87], 9, v33
	s_nop 0
	v_cndmask_b32_e64 v124, 0, 1.0, vcc
	v_cndmask_b32_e64 v125, 0, 1.0, s[86:87]
	v_cmp_eq_u32_e32 vcc, 10, v33
	v_cmp_eq_u32_e64 s[86:87], 11, v33
	s_nop 0
	v_cndmask_b32_e64 v126, 0, 1.0, vcc
	v_cndmask_b32_e64 v127, 0, 1.0, s[86:87]
	v_cmp_eq_u32_e32 vcc, 12, v33
	v_cmp_eq_u32_e64 s[86:87], 13, v33
	s_nop 0
	v_cndmask_b32_e64 v128, 0, 1.0, vcc
	v_cndmask_b32_e64 v129, 0, 1.0, s[86:87]
	v_cmp_eq_u32_e32 vcc, 14, v33
	v_cmp_eq_u32_e64 s[86:87], 15, v33
	s_nop 0
	v_cndmask_b32_e64 v130, 0, 1.0, vcc
	v_cndmask_b32_e64 v131, 0, 1.0, s[86:87]
	s_waitcnt lgkmcnt(0)
	v_fmac_f32_dpp v117, -v101, v116 row_newbcast:0 row_mask:0xf bank_mask:0xf
	v_fmac_f32_dpp v118, -v102, v116 row_newbcast:0 row_mask:0xf bank_mask:0xf
	v_fmac_f32_dpp v118, -v102, v117 row_newbcast:1 row_mask:0xf bank_mask:0xf
	v_fmac_f32_dpp v119, -v103, v116 row_newbcast:0 row_mask:0xf bank_mask:0xf
	v_fmac_f32_dpp v119, -v103, v117 row_newbcast:1 row_mask:0xf bank_mask:0xf
	v_fmac_f32_dpp v119, -v103, v118 row_newbcast:2 row_mask:0xf bank_mask:0xf
	v_mov_b32_e32 v92, 0
	v_fmac_f32_dpp v120, -v104, v116 row_newbcast:0 row_mask:0xf bank_mask:0xf
	v_fmac_f32_dpp v92, -v104, v117 row_newbcast:1 row_mask:0xf bank_mask:0xf
	v_fmac_f32_dpp v120, -v104, v118 row_newbcast:2 row_mask:0xf bank_mask:0xf
	v_fmac_f32_dpp v92, -v104, v119 row_newbcast:3 row_mask:0xf bank_mask:0xf
	v_add_f32_e32 v120, v120, v92
	v_mov_b32_e32 v92, 0
	v_fmac_f32_dpp v121, -v105, v116 row_newbcast:0 row_mask:0xf bank_mask:0xf
	v_fmac_f32_dpp v92, -v105, v117 row_newbcast:1 row_mask:0xf bank_mask:0xf
	v_fmac_f32_dpp v121, -v105, v118 row_newbcast:2 row_mask:0xf bank_mask:0xf
	v_fmac_f32_dpp v92, -v105, v119 row_newbcast:3 row_mask:0xf bank_mask:0xf
	v_fmac_f32_dpp v121, -v105, v120 row_newbcast:4 row_mask:0xf bank_mask:0xf
	v_add_f32_e32 v121, v121, v92
	v_mov_b32_e32 v92, 0
	v_fmac_f32_dpp v122, -v106, v116 row_newbcast:0 row_mask:0xf bank_mask:0xf
	v_fmac_f32_dpp v92, -v106, v117 row_newbcast:1 row_mask:0xf bank_mask:0xf
	v_fmac_f32_dpp v122, -v106, v118 row_newbcast:2 row_mask:0xf bank_mask:0xf
	v_fmac_f32_dpp v92, -v106, v119 row_newbcast:3 row_mask:0xf bank_mask:0xf
	v_fmac_f32_dpp v122, -v106, v120 row_newbcast:4 row_mask:0xf bank_mask:0xf
	v_fmac_f32_dpp v92, -v106, v121 row_newbcast:5 row_mask:0xf bank_mask:0xf
	v_add_f32_e32 v122, v122, v92
	v_mov_b32_e32 v92, 0
; #define LAS __attribute__((address_space(3)))
; __device__ __forceinline__ void phase_chunk_prep(const Params& p, LAS unsigned char* lds, int wave_s) {
;     ...
; #pragma unroll
;             for (int i = 0; i < 64; ++i) {
;                 float s0 = RHS[i * 256 + col], s1 = 0.f, s2 = 0.f, s3 = 0.f;
; #pragma unroll
;                 for (int j4 = 0; j4 < (i + 3) / 4; ++j4) { const f32x4 a = *(const LAS f32x4*)(AM + i * 64 + 4 * j4);
;                     s0 -= a.x * sol[4 * j4]; s1 -= a.y * sol[4 * j4 + 1]; s2 -= a.z * sol[4 * j4 + 2]; s3 -= a.w * sol[4 * j4 + 3]; }
;                 sol[i] = (s0 + s1) + (s2 + s3);
;             }
	v_fmac_f32_dpp v123, -v107, v116 row_newbcast:0 row_mask:0xf bank_mask:0xf
	v_fmac_f32_dpp v92, -v107, v117 row_newbcast:1 row_mask:0xf bank_mask:0xf
	v_fmac_f32_dpp v123, -v107, v118 row_newbcast:2 row_mask:0xf bank_mask:0xf
	v_fmac_f32_dpp v92, -v107, v119 row_newbcast:3 row_mask:0xf bank_mask:0xf
	v_fmac_f32_dpp v123, -v107, v120 row_newbcast:4 row_mask:0xf bank_mask:0xf
	v_fmac_f32_dpp v92, -v107, v121 row_newbcast:5 row_mask:0xf bank_mask:0xf
	v_fmac_f32_dpp v123, -v107, v122 row_newbcast:6 row_mask:0xf bank_mask:0xf
	v_add_f32_e32 v123, v123, v92
	v_mov_b32_e32 v92, 0
	v_fmac_f32_dpp v124, -v108, v116 row_newbcast:0 row_mask:0xf bank_mask:0xf
	v_fmac_f32_dpp v92, -v108, v117 row_newbcast:1 row_mask:0xf bank_mask:0xf
	v_fmac_f32_dpp v124, -v108, v118 row_newbcast:2 row_mask:0xf bank_mask:0xf
	v_fmac_f32_dpp v92, -v108, v119 row_newbcast:3 row_mask:0xf bank_mask:0xf
	v_fmac_f32_dpp v124, -v108, v120 row_newbcast:4 row_mask:0xf bank_mask:0xf
	v_fmac_f32_dpp v92, -v108, v121 row_newbcast:5 row_mask:0xf bank_mask:0xf
	v_fmac_f32_dpp v124, -v108, v122 row_newbcast:6 row_mask:0xf bank_mask:0xf
	v_fmac_f32_dpp v92, -v108, v123 row_newbcast:7 row_mask:0xf bank_mask:0xf
	v_add_f32_e32 v124, v124, v92
	v_mov_b32_e32 v92, 0
	v_fmac_f32_dpp v125, -v109, v116 row_newbcast:0 row_mask:0xf bank_mask:0xf
	v_fmac_f32_dpp v92, -v109, v117 row_newbcast:1 row_mask:0xf bank_mask:0xf
	v_fmac_f32_dpp v125, -v109, v118 row_newbcast:2 row_mask:0xf bank_mask:0xf
	v_fmac_f32_dpp v92, -v109, v119 row_newbcast:3 row_mask:0xf bank_mask:0xf
	v_fmac_f32_dpp v125, -v109, v120 row_newbcast:4 row_mask:0xf bank_mask:0xf
	v_fmac_f32_dpp v92, -v109, v121 row_newbcast:5 row_mask:0xf bank_mask:0xf
	v_fmac_f32_dpp v125, -v109, v122 row_newbcast:6 row_mask:0xf bank_mask:0xf
	v_fmac_f32_dpp v92, -v109, v123 row_newbcast:7 row_mask:0xf bank_mask:0xf
	v_fmac_f32_dpp v125, -v109, v124 row_newbcast:8 row_mask:0xf bank_mask:0xf
	v_add_f32_e32 v125, v125, v92
	v_mov_b32_e32 v92, 0
	v_fmac_f32_dpp v126, -v110, v116 row_newbcast:0 row_mask:0xf bank_mask:0xf
	v_fmac_f32_dpp v92, -v110, v117 row_newbcast:1 row_mask:0xf bank_mask:0xf
	v_fmac_f32_dpp v126, -v110, v118 row_newbcast:2 row_mask:0xf bank_mask:0xf
	v_fmac_f32_dpp v92, -v110, v119 row_newbcast:3 row_mask:0xf bank_mask:0xf
	v_fmac_f32_dpp v126, -v110, v120 row_newbcast:4 row_mask:0xf bank_mask:0xf
	v_fmac_f32_dpp v92, -v110, v121 row_newbcast:5 row_mask:0xf bank_mask:0xf
	v_fmac_f32_dpp v126, -v110, v122 row_newbcast:6 row_mask:0xf bank_mask:0xf
	v_fmac_f32_dpp v92, -v110, v123 row_newbcast:7 row_mask:0xf bank_mask:0xf
	v_fmac_f32_dpp v126, -v110, v124 row_newbcast:8 row_mask:0xf bank_mask:0xf
	v_fmac_f32_dpp v92, -v110, v125 row_newbcast:9 row_mask:0xf bank_mask:0xf
	v_add_f32_e32 v126, v126, v92
	v_mov_b32_e32 v92, 0
	v_fmac_f32_dpp v127, -v111, v116 row_newbcast:0 row_mask:0xf bank_mask:0xf
	v_fmac_f32_dpp v92, -v111, v117 row_newbcast:1 row_mask:0xf bank_mask:0xf
	v_fmac_f32_dpp v127, -v111, v118 row_newbcast:2 row_mask:0xf bank_mask:0xf
	v_fmac_f32_dpp v92, -v111, v119 row_newbcast:3 row_mask:0xf bank_mask:0xf
	v_fmac_f32_dpp v127, -v111, v120 row_newbcast:4 row_mask:0xf bank_mask:0xf
	v_fmac_f32_dpp v92, -v111, v121 row_newbcast:5 row_mask:0xf bank_mask:0xf
	v_fmac_f32_dpp v127, -v111, v122 row_newbcast:6 row_mask:0xf bank_mask:0xf
	v_fmac_f32_dpp v92, -v111, v123 row_newbcast:7 row_mask:0xf bank_mask:0xf
	v_fmac_f32_dpp v127, -v111, v124 row_newbcast:8 row_mask:0xf bank_mask:0xf
	v_fmac_f32_dpp v92, -v111, v125 row_newbcast:9 row_mask:0xf bank_mask:0xf
	v_fmac_f32_dpp v127, -v111, v126 row_newbcast:10 row_mask:0xf bank_mask:0xf
	v_add_f32_e32 v127, v127, v92
	v_mov_b32_e32 v92, 0
	v_fmac_f32_dpp v128, -v112, v116 row_newbcast:0 row_mask:0xf bank_mask:0xf
	v_fmac_f32_dpp v92, -v112, v117 row_newbcast:1 row_mask:0xf bank_mask:0xf
	v_fmac_f32_dpp v128, -v112, v118 row_newbcast:2 row_mask:0xf bank_mask:0xf
	v_fmac_f32_dpp v92, -v112, v119 row_newbcast:3 row_mask:0xf bank_mask:0xf
	v_fmac_f32_dpp v128, -v112, v120 row_newbcast:4 row_mask:0xf bank_mask:0xf
	v_fmac_f32_dpp v92, -v112, v121 row_newbcast:5 row_mask:0xf bank_mask:0xf
	v_fmac_f32_dpp v128, -v112, v122 row_newbcast:6 row_mask:0xf bank_mask:0xf
	v_fmac_f32_dpp v92, -v112, v123 row_newbcast:7 row_mask:0xf bank_mask:0xf
	v_fmac_f32_dpp v128, -v112, v124 row_newbcast:8 row_mask:0xf bank_mask:0xf
	v_fmac_f32_dpp v92, -v112, v125 row_newbcast:9 row_mask:0xf bank_mask:0xf
	v_fmac_f32_dpp v128, -v112, v126 row_newbcast:10 row_mask:0xf bank_mask:0xf
	v_fmac_f32_dpp v92, -v112, v127 row_newbcast:11 row_mask:0xf bank_mask:0xf
	v_add_f32_e32 v128, v128, v92
	v_mov_b32_e32 v92, 0
	v_fmac_f32_dpp v129, -v113, v116 row_newbcast:0 row_mask:0xf bank_mask:0xf
	v_fmac_f32_dpp v92, -v113, v117 row_newbcast:1 row_mask:0xf bank_mask:0xf
	v_fmac_f32_dpp v129, -v113, v118 row_newbcast:2 row_mask:0xf bank_mask:0xf
	v_fmac_f32_dpp v92, -v113, v119 row_newbcast:3 row_mask:0xf bank_mask:0xf
	v_fmac_f32_dpp v129, -v113, v120 row_newbcast:4 row_mask:0xf bank_mask:0xf
	v_fmac_f32_dpp v92, -v113, v121 row_newbcast:5 row_mask:0xf bank_mask:0xf
	v_fmac_f32_dpp v129, -v113, v122 row_newbcast:6 row_mask:0xf bank_mask:0xf
	v_fmac_f32_dpp v92, -v113, v123 row_newbcast:7 row_mask:0xf bank_mask:0xf
	v_fmac_f32_dpp v129, -v113, v124 row_newbcast:8 row_mask:0xf bank_mask:0xf
	v_fmac_f32_dpp v92, -v113, v125 row_newbcast:9 row_mask:0xf bank_mask:0xf
	v_fmac_f32_dpp v129, -v113, v126 row_newbcast:10 row_mask:0xf bank_mask:0xf
	v_fmac_f32_dpp v92, -v113, v127 row_newbcast:11 row_mask:0xf bank_mask:0xf
	v_fmac_f32_dpp v129, -v113, v128 row_newbcast:12 row_mask:0xf bank_mask:0xf
	v_add_f32_e32 v129, v129, v92
; #define LAS __attribute__((address_space(3)))
; __device__ __forceinline__ void phase_chunk_prep(const Params& p, LAS unsigned char* lds, int wave_s) {
;     ...
;         if (tid < 256) {
;             const int col = tid; float sol[64];
; #pragma unroll
;             for (int i = 0; i < 64; ++i) sol[i] = 0.f;
; #pragma unroll
;             for (int i = 0; i < 64; ++i) {
;                 float s0 = RHS[i * 256 + col], s1 = 0.f, s2 = 0.f, s3 = 0.f;
; #pragma unroll
;                 for (int j4 = 0; j4 < (i + 3) / 4; ++j4) { const f32x4 a = *(const LAS f32x4*)(AM + i * 64 + 4 * j4);
;                     s0 -= a.x * sol[4 * j4]; s1 -= a.y * sol[4 * j4 + 1]; s2 -= a.z * sol[4 * j4 + 2]; s3 -= a.w * sol[4 * j4 + 3]; }
;                 sol[i] = (s0 + s1) + (s2 + s3);
;             }
	v_mov_b32_e32 v92, 0
	v_fmac_f32_dpp v130, -v114, v116 row_newbcast:0 row_mask:0xf bank_mask:0xf
	v_fmac_f32_dpp v92, -v114, v117 row_newbcast:1 row_mask:0xf bank_mask:0xf
	v_fmac_f32_dpp v130, -v114, v118 row_newbcast:2 row_mask:0xf bank_mask:0xf
	v_fmac_f32_dpp v92, -v114, v119 row_newbcast:3 row_mask:0xf bank_mask:0xf
	v_fmac_f32_dpp v130, -v114, v120 row_newbcast:4 row_mask:0xf bank_mask:0xf
	v_fmac_f32_dpp v92, -v114, v121 row_newbcast:5 row_mask:0xf bank_mask:0xf
	v_fmac_f32_dpp v130, -v114, v122 row_newbcast:6 row_mask:0xf bank_mask:0xf
	v_fmac_f32_dpp v92, -v114, v123 row_newbcast:7 row_mask:0xf bank_mask:0xf
	v_fmac_f32_dpp v130, -v114, v124 row_newbcast:8 row_mask:0xf bank_mask:0xf
	v_fmac_f32_dpp v92, -v114, v125 row_newbcast:9 row_mask:0xf bank_mask:0xf
	v_fmac_f32_dpp v130, -v114, v126 row_newbcast:10 row_mask:0xf bank_mask:0xf
	v_fmac_f32_dpp v92, -v114, v127 row_newbcast:11 row_mask:0xf bank_mask:0xf
	v_fmac_f32_dpp v130, -v114, v128 row_newbcast:12 row_mask:0xf bank_mask:0xf
	v_fmac_f32_dpp v92, -v114, v129 row_newbcast:13 row_mask:0xf bank_mask:0xf
	v_add_f32_e32 v130, v130, v92
	v_mov_b32_e32 v92, 0
	v_fmac_f32_dpp v131, -v115, v116 row_newbcast:0 row_mask:0xf bank_mask:0xf
	v_fmac_f32_dpp v92, -v115, v117 row_newbcast:1 row_mask:0xf bank_mask:0xf
	v_fmac_f32_dpp v131, -v115, v118 row_newbcast:2 row_mask:0xf bank_mask:0xf
	v_fmac_f32_dpp v92, -v115, v119 row_newbcast:3 row_mask:0xf bank_mask:0xf
	v_fmac_f32_dpp v131, -v115, v120 row_newbcast:4 row_mask:0xf bank_mask:0xf
	v_fmac_f32_dpp v92, -v115, v121 row_newbcast:5 row_mask:0xf bank_mask:0xf
	v_fmac_f32_dpp v131, -v115, v122 row_newbcast:6 row_mask:0xf bank_mask:0xf
	v_fmac_f32_dpp v92, -v115, v123 row_newbcast:7 row_mask:0xf bank_mask:0xf
	v_fmac_f32_dpp v131, -v115, v124 row_newbcast:8 row_mask:0xf bank_mask:0xf
	v_fmac_f32_dpp v92, -v115, v125 row_newbcast:9 row_mask:0xf bank_mask:0xf
	v_fmac_f32_dpp v131, -v115, v126 row_newbcast:10 row_mask:0xf bank_mask:0xf
	v_fmac_f32_dpp v92, -v115, v127 row_newbcast:11 row_mask:0xf bank_mask:0xf
	v_fmac_f32_dpp v131, -v115, v128 row_newbcast:12 row_mask:0xf bank_mask:0xf
	v_fmac_f32_dpp v92, -v115, v129 row_newbcast:13 row_mask:0xf bank_mask:0xf
	v_fmac_f32_dpp v131, -v115, v130 row_newbcast:14 row_mask:0xf bank_mask:0xf
	v_add_f32_e32 v131, v131, v92
	ds_write_b32 v87, v116
	ds_write_b32 v87, v117 offset:80
	ds_write_b32 v87, v118 offset:160
	ds_write_b32 v87, v119 offset:240
	ds_write_b32 v87, v120 offset:320
	ds_write_b32 v87, v121 offset:400
	ds_write_b32 v87, v122 offset:480
	ds_write_b32 v87, v123 offset:560
	ds_write_b32 v87, v124 offset:640
	ds_write_b32 v87, v125 offset:720
	ds_write_b32 v87, v126 offset:800
	ds_write_b32 v87, v127 offset:880
	ds_write_b32 v87, v128 offset:960
	ds_write_b32 v87, v129 offset:1040
	ds_write_b32 v87, v130 offset:1120
	ds_write_b32 v87, v131 offset:1200
.Lfm_not0:
	s_waitcnt lgkmcnt(0)
	s_barrier
	ds_read_b128 v[132:135], v86
	ds_read_b128 v[136:139], v86 offset:1280
	ds_read_b128 v[140:143], v86 offset:2560
	ds_read_b128 v[144:147], v86 offset:3840
	v_xor_b32_e32 v148, 0x80000000, v148
	v_xor_b32_e32 v149, 0x80000000, v149
	v_xor_b32_e32 v150, 0x80000000, v150
	v_xor_b32_e32 v151, 0x80000000, v151
	v_xor_b32_e32 v152, 0x80000000, v152
	v_xor_b32_e32 v153, 0x80000000, v153
	v_xor_b32_e32 v154, 0x80000000, v154
	v_xor_b32_e32 v155, 0x80000000, v155
	v_xor_b32_e32 v156, 0x80000000, v156
	v_xor_b32_e32 v157, 0x80000000, v157
	v_xor_b32_e32 v158, 0x80000000, v158
	v_xor_b32_e32 v159, 0x80000000, v159
	v_xor_b32_e32 v160, 0x80000000, v160
	v_xor_b32_e32 v161, 0x80000000, v161
	v_xor_b32_e32 v162, 0x80000000, v162
	v_xor_b32_e32 v163, 0x80000000, v163
	v_xor_b32_e32 v164, 0x80000000, v164
	v_xor_b32_e32 v165, 0x80000000, v165
	v_xor_b32_e32 v166, 0x80000000, v166
	v_xor_b32_e32 v167, 0x80000000, v167
	v_xor_b32_e32 v168, 0x80000000, v168
	v_xor_b32_e32 v169, 0x80000000, v169
	v_xor_b32_e32 v170, 0x80000000, v170
	v_xor_b32_e32 v171, 0x80000000, v171
	s_waitcnt lgkmcnt(0)
	v_mfma_f32_16x16x4_f32 v[36:39], v132, v0, 0
	v_mfma_f32_16x16x4_f32 v[36:39], v133, v1, v[36:39]
	v_mfma_f32_16x16x4_f32 v[36:39], v134, v2, v[36:39]
	v_mfma_f32_16x16x4_f32 v[36:39], v135, v3, v[36:39]
	v_mfma_f32_16x16x4_f32 v[68:71], v132, v16, 0
	v_mfma_f32_16x16x4_f32 v[68:71], v133, v17, v[68:71]
	v_mfma_f32_16x16x4_f32 v[68:71], v134, v18, v[68:71]
	v_mfma_f32_16x16x4_f32 v[68:71], v135, v19, v[68:71]
	v_mfma_f32_16x16x4_f32 v[4:7], v148, v36, v[4:7]
	v_mfma_f32_16x16x4_f32 v[4:7], v149, v37, v[4:7]
	v_mfma_f32_16x16x4_f32 v[4:7], v150, v38, v[4:7]
	v_mfma_f32_16x16x4_f32 v[4:7], v151, v39, v[4:7]
	v_mfma_f32_16x16x4_f32 v[8:11], v152, v36, v[8:11]
	v_mfma_f32_16x16x4_f32 v[8:11], v153, v37, v[8:11]
	v_mfma_f32_16x16x4_f32 v[8:11], v154, v38, v[8:11]
	v_mfma_f32_16x16x4_f32 v[8:11], v155, v39, v[8:11]
	v_mfma_f32_16x16x4_f32 v[12:15], v160, v36, v[12:15]
	v_mfma_f32_16x16x4_f32 v[12:15], v161, v37, v[12:15]
	v_mfma_f32_16x16x4_f32 v[12:15], v162, v38, v[12:15]
	v_mfma_f32_16x16x4_f32 v[12:15], v163, v39, v[12:15]
	v_mfma_f32_16x16x4_f32 v[20:23], v148, v68, v[20:23]
	v_mfma_f32_16x16x4_f32 v[20:23], v149, v69, v[20:23]
	v_mfma_f32_16x16x4_f32 v[20:23], v150, v70, v[20:23]
	v_mfma_f32_16x16x4_f32 v[20:23], v151, v71, v[20:23]
	v_mfma_f32_16x16x4_f32 v[24:27], v152, v68, v[24:27]
	v_mfma_f32_16x16x4_f32 v[24:27], v153, v69, v[24:27]
	v_mfma_f32_16x16x4_f32 v[24:27], v154, v70, v[24:27]
	v_mfma_f32_16x16x4_f32 v[24:27], v155, v71, v[24:27]
	v_mfma_f32_16x16x4_f32 v[28:31], v160, v68, v[28:31]
	v_mfma_f32_16x16x4_f32 v[28:31], v161, v69, v[28:31]
	v_mfma_f32_16x16x4_f32 v[28:31], v162, v70, v[28:31]
; #define LAS __attribute__((address_space(3)))
; __device__ __forceinline__ bf16_t f2bf(float x) { return (bf16_t)(pk2(x, 0.f) & 0xffffu); }
; __device__ __forceinline__ void phase_chunk_prep(const Params& p, LAS unsigned char* lds, int wave_s) {
;     ...
;             for (int i = 0; i < 64; ++i) {
;                 float s0 = RHS[i * 256 + col], s1 = 0.f, s2 = 0.f, s3 = 0.f;
; #pragma unroll
;                 for (int j4 = 0; j4 < (i + 3) / 4; ++j4) { const f32x4 a = *(const LAS f32x4*)(AM + i * 64 + 4 * j4);
;                     s0 -= a.x * sol[4 * j4]; s1 -= a.y * sol[4 * j4 + 1]; s2 -= a.z * sol[4 * j4 + 2]; s3 -= a.w * sol[4 * j4 + 3]; }
;                 sol[i] = (s0 + s1) + (s2 + s3);
;             }
;             if (col < 128) {
; #pragma unroll
;                 for (int mm = 0; mm < 4; ++mm)
; #pragma unroll
;                     for (int q4 = 0; q4 < 4; ++q4)
;                         *(f32x4*)(U + ((((col >> 4) * 4 + mm) * 64 + q4 * 16 + (col & 15)) << 2)) = (f32x4){sol[16 * mm + 4 * q4], sol[16 * mm + 4 * q4 + 1], sol[16 * mm + 4 * q4 + 2], sol[16 * mm + 4 * q4 + 3]};
;             } else {
; #pragma unroll
;                 for (int i = 0; i < 64; ++i) img[IMG_WD + i * SWD + (col - 128)] = f2bf(sol[i]);
;             }
	v_mfma_f32_16x16x4_f32 v[28:31], v163, v71, v[28:31]
	v_mfma_f32_16x16x4_f32 v[40:43], v136, v4, 0
	v_mfma_f32_16x16x4_f32 v[40:43], v137, v5, v[40:43]
	v_mfma_f32_16x16x4_f32 v[40:43], v138, v6, v[40:43]
	v_mfma_f32_16x16x4_f32 v[40:43], v139, v7, v[40:43]
	v_mfma_f32_16x16x4_f32 v[72:75], v136, v20, 0
	v_mfma_f32_16x16x4_f32 v[72:75], v137, v21, v[72:75]
	v_mfma_f32_16x16x4_f32 v[72:75], v138, v22, v[72:75]
	v_mfma_f32_16x16x4_f32 v[72:75], v139, v23, v[72:75]
	v_mfma_f32_16x16x4_f32 v[8:11], v156, v40, v[8:11]
	v_mfma_f32_16x16x4_f32 v[8:11], v157, v41, v[8:11]
	v_mfma_f32_16x16x4_f32 v[8:11], v158, v42, v[8:11]
	v_mfma_f32_16x16x4_f32 v[8:11], v159, v43, v[8:11]
	v_mfma_f32_16x16x4_f32 v[12:15], v164, v40, v[12:15]
	v_mfma_f32_16x16x4_f32 v[12:15], v165, v41, v[12:15]
	v_mfma_f32_16x16x4_f32 v[12:15], v166, v42, v[12:15]
	v_mfma_f32_16x16x4_f32 v[12:15], v167, v43, v[12:15]
	v_mfma_f32_16x16x4_f32 v[24:27], v156, v72, v[24:27]
	v_mfma_f32_16x16x4_f32 v[24:27], v157, v73, v[24:27]
	v_mfma_f32_16x16x4_f32 v[24:27], v158, v74, v[24:27]
	v_mfma_f32_16x16x4_f32 v[24:27], v159, v75, v[24:27]
	v_mfma_f32_16x16x4_f32 v[28:31], v164, v72, v[28:31]
	v_mfma_f32_16x16x4_f32 v[28:31], v165, v73, v[28:31]
	v_mfma_f32_16x16x4_f32 v[28:31], v166, v74, v[28:31]
	v_mfma_f32_16x16x4_f32 v[28:31], v167, v75, v[28:31]
	v_mfma_f32_16x16x4_f32 v[44:47], v140, v8, 0
	v_mfma_f32_16x16x4_f32 v[44:47], v141, v9, v[44:47]
	v_mfma_f32_16x16x4_f32 v[44:47], v142, v10, v[44:47]
	v_mfma_f32_16x16x4_f32 v[44:47], v143, v11, v[44:47]
	v_mfma_f32_16x16x4_f32 v[76:79], v140, v24, 0
	v_mfma_f32_16x16x4_f32 v[76:79], v141, v25, v[76:79]
	v_mfma_f32_16x16x4_f32 v[76:79], v142, v26, v[76:79]
	v_mfma_f32_16x16x4_f32 v[76:79], v143, v27, v[76:79]
	v_mfma_f32_16x16x4_f32 v[12:15], v168, v44, v[12:15]
	v_mfma_f32_16x16x4_f32 v[12:15], v169, v45, v[12:15]
	v_mfma_f32_16x16x4_f32 v[12:15], v170, v46, v[12:15]
	v_mfma_f32_16x16x4_f32 v[12:15], v171, v47, v[12:15]
	v_mfma_f32_16x16x4_f32 v[28:31], v168, v76, v[28:31]
	v_mfma_f32_16x16x4_f32 v[28:31], v169, v77, v[28:31]
	v_mfma_f32_16x16x4_f32 v[28:31], v170, v78, v[28:31]
	v_mfma_f32_16x16x4_f32 v[28:31], v171, v79, v[28:31]
	v_mfma_f32_16x16x4_f32 v[48:51], v144, v12, 0
	v_mfma_f32_16x16x4_f32 v[48:51], v145, v13, v[48:51]
	v_mfma_f32_16x16x4_f32 v[48:51], v146, v14, v[48:51]
	v_mfma_f32_16x16x4_f32 v[48:51], v147, v15, v[48:51]
	v_mfma_f32_16x16x4_f32 v[80:83], v144, v28, 0
	v_mfma_f32_16x16x4_f32 v[80:83], v145, v29, v[80:83]
	v_mfma_f32_16x16x4_f32 v[80:83], v146, v30, v[80:83]
	v_mfma_f32_16x16x4_f32 v[80:83], v147, v31, v[80:83]
	s_cmp_gt_u32 s84, 3
	s_cbranch_scc1 .Lfm_w
	s_lshl_b32 s96, s16, 15
	s_add_u32 s96, s20, s96
	s_addc_u32 s97, s21, 0
	s_lshl_b32 s85, s84, 13
	v_lshl_add_u32 v89, v34, 8, s85
	v_lshl_add_u32 v89, v33, 4, v89
	v_add_u32_e32 v90, 0x1000, v89
	global_store_dwordx4 v89, v[36:39], s[96:97]
	global_store_dwordx4 v89, v[40:43], s[96:97] offset:1024
	global_store_dwordx4 v89, v[44:47], s[96:97] offset:2048
	global_store_dwordx4 v89, v[48:51], s[96:97] offset:3072
	global_store_dwordx4 v90, v[68:71], s[96:97]
	global_store_dwordx4 v90, v[72:75], s[96:97] offset:1024
	global_store_dwordx4 v90, v[76:79], s[96:97] offset:2048
	s_nop 7
	s_nop 1
	global_store_dwordx4 v90, v[80:83], s[96:97] offset:3072
	s_waitcnt vmcnt(8)
	s_branch .LBB0_663
.Lfm_w:
	s_sub_i32 s85, s84, 4
	s_lshl_b32 s85, s85, 6
	v_mul_u32_u24_e32 v91, 0x420, v34
	v_lshl_add_u32 v91, v33, 1, v91
	v_add_u32_e32 v91, s85, v91
	s_mov_b64 s[96:97], s[30:31]
	v_cvt_pk_bf16_f32 v92, v36, v36
	global_store_short v91, v92, s[96:97]
	v_cvt_pk_bf16_f32 v92, v37, v37
	global_store_short v91, v92, s[96:97] offset:264
	v_cvt_pk_bf16_f32 v92, v38, v38
	global_store_short v91, v92, s[96:97] offset:528
	v_cvt_pk_bf16_f32 v92, v39, v39
	global_store_short v91, v92, s[96:97] offset:792
	v_cvt_pk_bf16_f32 v92, v68, v68
	global_store_short v91, v92, s[96:97] offset:32
	v_cvt_pk_bf16_f32 v92, v69, v69
	global_store_short v91, v92, s[96:97] offset:296
	v_cvt_pk_bf16_f32 v92, v70, v70
	global_store_short v91, v92, s[96:97] offset:560
	v_cvt_pk_bf16_f32 v92, v71, v71
	global_store_short v91, v92, s[96:97] offset:824
	s_add_u32 s96, s96, 0x1080
	s_addc_u32 s97, s97, 0
	v_cvt_pk_bf16_f32 v92, v40, v40
	global_store_short v91, v92, s[96:97]
	v_cvt_pk_bf16_f32 v92, v41, v41
	global_store_short v91, v92, s[96:97] offset:264
	v_cvt_pk_bf16_f32 v92, v42, v42
	global_store_short v91, v92, s[96:97] offset:528
	v_cvt_pk_bf16_f32 v92, v43, v43
	global_store_short v91, v92, s[96:97] offset:792
	v_cvt_pk_bf16_f32 v92, v72, v72
	global_store_short v91, v92, s[96:97] offset:32
	v_cvt_pk_bf16_f32 v92, v73, v73
	global_store_short v91, v92, s[96:97] offset:296
	v_cvt_pk_bf16_f32 v92, v74, v74
	global_store_short v91, v92, s[96:97] offset:560
	v_cvt_pk_bf16_f32 v92, v75, v75
	global_store_short v91, v92, s[96:97] offset:824
	s_add_u32 s96, s96, 0x1080
	s_addc_u32 s97, s97, 0
	v_cvt_pk_bf16_f32 v92, v44, v44
	global_store_short v91, v92, s[96:97]
	v_cvt_pk_bf16_f32 v92, v45, v45
	global_store_short v91, v92, s[96:97] offset:264
	v_cvt_pk_bf16_f32 v92, v46, v46
	global_store_short v91, v92, s[96:97] offset:528
	v_cvt_pk_bf16_f32 v92, v47, v47
	global_store_short v91, v92, s[96:97] offset:792
	v_cvt_pk_bf16_f32 v92, v76, v76
	global_store_short v91, v92, s[96:97] offset:32
	v_cvt_pk_bf16_f32 v92, v77, v77
	global_store_short v91, v92, s[96:97] offset:296
	v_cvt_pk_bf16_f32 v92, v78, v78
	global_store_short v91, v92, s[96:97] offset:560
	v_cvt_pk_bf16_f32 v92, v79, v79
	global_store_short v91, v92, s[96:97] offset:824
	s_add_u32 s96, s96, 0x1080
	s_addc_u32 s97, s97, 0
	v_cvt_pk_bf16_f32 v92, v48, v48
	global_store_short v91, v92, s[96:97]
	v_cvt_pk_bf16_f32 v92, v49, v49
	global_store_short v91, v92, s[96:97] offset:264
	v_cvt_pk_bf16_f32 v92, v50, v50
	global_store_short v91, v92, s[96:97] offset:528
	v_cvt_pk_bf16_f32 v92, v51, v51
	global_store_short v91, v92, s[96:97] offset:792
	s_nop 3
	v_cvt_pk_bf16_f32 v92, v80, v80
	global_store_short v91, v92, s[96:97] offset:32
	v_cvt_pk_bf16_f32 v92, v81, v81
	global_store_short v91, v92, s[96:97] offset:296
	v_cvt_pk_bf16_f32 v92, v82, v82
	global_store_short v91, v92, s[96:97] offset:560
	v_cvt_pk_bf16_f32 v92, v83, v83
	global_store_short v91, v92, s[96:97] offset:824
	s_waitcnt vmcnt(32)
	s_branch .LBB0_663
